# head2: stack4 + attention steady loop step 2: first 5 adds + 2 cvts moved in front of the segment's first MFMA (gap 1 carries 4 VALU instead of 11)
# speedup vs baseline: 1.0200x; 1.0002x over previous
.LBB0_413:
	s_mov_b32 s16, s26
	s_mov_b32 s2, s18
	s_mov_b32 s3, s24
	v_lshl_add_u32 v69, s17, 1, v232
	ds_read_b64_tr_b16 v[76:77], v69 offset:24576
	ds_read_b64_tr_b16 v[78:79], v69 offset:25088
	v_add_f32_e32 v72, v100, v101
	v_add_f32_e32 v72, v102, v72
	v_add_f32_e32 v72, v103, v72
	v_add_f32_e32 v72, v104, v72
	v_add_f32_e32 v72, v105, v72
	v_cvt_pk_bf16_f32 v160, v100, v101
	v_cvt_pk_bf16_f32 v161, v102, v103
	s_waitcnt lgkmcnt(9)
	v_mfma_f32_32x32x16_bf16 v[132:147], v[208:211], v[176:179], 0
	v_add_f32_e32 v72, v106, v72
	v_add_f32_e32 v72, v107, v72
	v_add_f32_e32 v72, v108, v72
	v_add_f32_e32 v72, v109, v72
	v_cvt_pk_bf16_f32 v162, v104, v105
	v_cvt_pk_bf16_f32 v163, v106, v107
	s_waitcnt lgkmcnt(8)
	v_mfma_f32_32x32x16_bf16 v[116:131], v[200:203], v[176:179], 0
	ds_read_b64_tr_b16 v[80:81], v69 offset:25600
	ds_read_b64_tr_b16 v[82:83], v69 offset:26112
	v_add_f32_e32 v72, v110, v72
	v_add_f32_e32 v72, v111, v72
	v_add_f32_e32 v72, v112, v72
	v_add_f32_e32 v72, v113, v72
	v_cvt_pk_bf16_f32 v156, v108, v109
	v_cvt_pk_bf16_f32 v157, v110, v111
	s_waitcnt lgkmcnt(9)
	v_mfma_f32_32x32x16_bf16 v[132:147], v[204:207], v[172:175], v[132:147]
	v_add_f32_e32 v72, v114, v72
	v_add_f32_e32 v72, v115, v72
	v_add_f32_e32 v72, v84, v72
	v_add_f32_e32 v72, v85, v72
	v_cvt_pk_bf16_f32 v158, v112, v113
	v_cvt_pk_bf16_f32 v159, v114, v115
	s_waitcnt lgkmcnt(8)
	v_mfma_f32_32x32x16_bf16 v[116:131], v[196:199], v[172:175], v[116:131]
	ds_read_b64_tr_b16 v[100:101], v69 offset:26624
	ds_read_b64_tr_b16 v[102:103], v69 offset:27136
	v_add_f32_e32 v72, v86, v72
	v_add_f32_e32 v72, v87, v72
	v_add_f32_e32 v72, v88, v72
	v_add_f32_e32 v72, v89, v72
	v_cvt_pk_bf16_f32 v152, v84, v85
	v_cvt_pk_bf16_f32 v153, v86, v87
	s_waitcnt lgkmcnt(9)
	v_mfma_f32_32x32x16_bf16 v[132:147], v[192:195], v[168:171], v[132:147]
	v_add_f32_e32 v72, v90, v72
	v_add_f32_e32 v72, v91, v72
	v_add_f32_e32 v72, v92, v72
	v_add_f32_e32 v72, v93, v72
	v_cvt_pk_bf16_f32 v154, v88, v89
	v_cvt_pk_bf16_f32 v155, v90, v91
	s_waitcnt lgkmcnt(8)
	v_mfma_f32_32x32x16_bf16 v[116:131], v[188:191], v[168:171], v[116:131]
	ds_read_b64_tr_b16 v[84:85], v69 offset:27648
	ds_read_b64_tr_b16 v[86:87], v69 offset:28160
	v_add_f32_e32 v72, v94, v72
	v_add_f32_e32 v72, v95, v72
	v_add_f32_e32 v72, v96, v72
	v_add_f32_e32 v72, v97, v72
	v_cvt_pk_bf16_f32 v148, v92, v93
	v_cvt_pk_bf16_f32 v149, v94, v95
	s_waitcnt lgkmcnt(9)
	v_mfma_f32_32x32x16_bf16 v[132:147], v[184:187], v[164:167], v[132:147]
	v_add_f32_e32 v72, v98, v72
	v_add_f32_e32 v72, v99, v72
	v_add_f32_e32 v72, 0, v72
	v_cvt_pk_bf16_f32 v150, v96, v97
	v_cvt_pk_bf16_f32 v151, v98, v99
	s_waitcnt lgkmcnt(8)
	v_mfma_f32_32x32x16_bf16 v[116:131], v[180:183], v[164:167], v[116:131]
	v_lshl_add_u64 v[74:75], v[0:1], 0, s[14:15]
	v_add_f32_e32 v68, v68, v72
	s_add_i32 m0, s24, s0
	v_lshl_add_u64 v[72:73], v[74:75], 0, s[76:77]
	global_load_lds_dwordx4 v[72:73], off
	s_lshl_b32 s17, s26, 1
	s_add_i32 s17, s17, s1
	s_mov_b32 m0, s17
	v_lshl_add_u64 v[72:73], v[70:71], 0, s[14:15]
	v_lshl_add_u64 v[88:89], v[72:73], 0, s[90:91]
	global_load_lds_dwordx4 v[88:89], off
	s_add_i32 m0, s17, 0x2000
	v_lshl_add_u64 v[88:89], v[72:73], 0, s[92:93]
	global_load_lds_dwordx4 v[88:89], off
	s_waitcnt lgkmcnt(6)
	v_mfma_f32_32x32x16_bf16 v[36:51], v[160:163], v[76:79], v[36:51]
	v_exp_f32_e32 v132, v132
	v_exp_f32_e32 v133, v133
	ds_read_b64_tr_b16 v[76:77], v69 offset:28672
	ds_read_b64_tr_b16 v[78:79], v69 offset:29184
	s_waitcnt lgkmcnt(6)
	v_mfma_f32_32x32x16_bf16 v[36:51], v[156:159], v[80:83], v[36:51]
	v_exp_f32_e32 v134, v134
	v_exp_f32_e32 v135, v135
	ds_read_b64_tr_b16 v[80:81], v69 offset:29696
	ds_read_b64_tr_b16 v[82:83], v69 offset:30208
	s_waitcnt lgkmcnt(6)
	v_mfma_f32_32x32x16_bf16 v[36:51], v[152:155], v[100:103], v[36:51]
	v_exp_f32_e32 v136, v136
	v_exp_f32_e32 v137, v137
	ds_read_b64_tr_b16 v[88:89], v69 offset:30720
	ds_read_b64_tr_b16 v[90:91], v69 offset:31232
	s_waitcnt lgkmcnt(6)
	v_mfma_f32_32x32x16_bf16 v[36:51], v[148:151], v[84:87], v[36:51]
	v_exp_f32_e32 v138, v138
	v_exp_f32_e32 v139, v139
	ds_read_b64_tr_b16 v[84:85], v69 offset:31744
	ds_read_b64_tr_b16 v[86:87], v69 offset:32256
	s_waitcnt lgkmcnt(6)
	v_mfma_f32_32x32x16_bf16 v[52:67], v[160:163], v[76:79], v[52:67]
	v_exp_f32_e32 v140, v140
	v_exp_f32_e32 v141, v141
	ds_read_b64_tr_b16 v[76:77], v69 offset:32768
	ds_read_b64_tr_b16 v[78:79], v69 offset:33280
	s_waitcnt lgkmcnt(6)
	v_mfma_f32_32x32x16_bf16 v[52:67], v[156:159], v[80:83], v[52:67]
	v_exp_f32_e32 v142, v142
	v_exp_f32_e32 v143, v143
	ds_read_b64_tr_b16 v[80:81], v69 offset:33792
	ds_read_b64_tr_b16 v[82:83], v69 offset:34304
	s_waitcnt lgkmcnt(6)
	v_mfma_f32_32x32x16_bf16 v[52:67], v[152:155], v[88:91], v[52:67]
	v_exp_f32_e32 v144, v144
	v_exp_f32_e32 v145, v145
	ds_read_b64_tr_b16 v[88:89], v69 offset:34816
	ds_read_b64_tr_b16 v[90:91], v69 offset:35328
	s_waitcnt lgkmcnt(6)
	v_mfma_f32_32x32x16_bf16 v[52:67], v[148:151], v[84:87], v[52:67]
	v_exp_f32_e32 v146, v146
	v_exp_f32_e32 v147, v147
	ds_read_b64_tr_b16 v[84:85], v69 offset:35840
	ds_read_b64_tr_b16 v[86:87], v69 offset:36352
	s_waitcnt lgkmcnt(6)
	v_mfma_f32_32x32x16_bf16 v[4:19], v[160:163], v[76:79], v[4:19]
	v_exp_f32_e32 v116, v116
	v_exp_f32_e32 v117, v117
	ds_read_b64_tr_b16 v[76:77], v69 offset:36864
	ds_read_b64_tr_b16 v[78:79], v69 offset:37376
	s_waitcnt lgkmcnt(6)
	v_mfma_f32_32x32x16_bf16 v[4:19], v[156:159], v[80:83], v[4:19]
	v_exp_f32_e32 v118, v118
	v_exp_f32_e32 v119, v119
	ds_read_b64_tr_b16 v[80:81], v69 offset:37888
	ds_read_b64_tr_b16 v[82:83], v69 offset:38400
	s_waitcnt lgkmcnt(6)
	v_mfma_f32_32x32x16_bf16 v[4:19], v[152:155], v[88:91], v[4:19]
	v_exp_f32_e32 v120, v120
	v_exp_f32_e32 v121, v121
	ds_read_b64_tr_b16 v[88:89], v69 offset:38912
	ds_read_b64_tr_b16 v[90:91], v69 offset:39424
	s_waitcnt lgkmcnt(6)
	v_mfma_f32_32x32x16_bf16 v[4:19], v[148:151], v[84:87], v[4:19]
	v_exp_f32_e32 v122, v122
	v_exp_f32_e32 v123, v123
	ds_read_b64_tr_b16 v[84:85], v69 offset:39936
	ds_read_b64_tr_b16 v[86:87], v69 offset:40448
	v_add_u32_e32 v69, s16, v230
	ds_read_b128 v[92:95], v69
	ds_read_b128 v[96:99], v69 offset:512
	s_waitcnt lgkmcnt(8)
	v_mfma_f32_32x32x16_bf16 v[20:35], v[160:163], v[76:79], v[20:35]
	v_exp_f32_e32 v124, v124
	v_exp_f32_e32 v125, v125
	ds_read_b128 v[76:79], v69 offset:2048
	ds_read_b128 v[180:183], v69 offset:2560
	s_waitcnt lgkmcnt(8)
	v_mfma_f32_32x32x16_bf16 v[20:35], v[156:159], v[80:83], v[20:35]
	v_exp_f32_e32 v126, v126
	v_exp_f32_e32 v127, v127
	ds_read_b128 v[80:83], v69 offset:4096
	ds_read_b128 v[184:187], v69 offset:4608
	ds_read_b128 v[188:191], v69 offset:6144
	ds_read_b128 v[192:195], v69 offset:6656
	s_waitcnt lgkmcnt(10)
	v_mfma_f32_32x32x16_bf16 v[20:35], v[152:155], v[88:91], v[20:35]
	v_exp_f32_e32 v128, v128
	v_exp_f32_e32 v129, v129
	s_waitcnt lgkmcnt(8)
	v_mfma_f32_32x32x16_bf16 v[20:35], v[148:151], v[84:87], v[20:35]
	v_exp_f32_e32 v130, v130
	v_exp_f32_e32 v131, v131
	s_add_i32 s17, s26, 0x2000
	s_cmpk_lg_i32 s26, 0x4000
	s_cselect_b32 s24, s17, 0
	v_lshl_add_u32 v69, s3, 1, v232
	s_waitcnt vmcnt(3) lgkmcnt(0)
	s_barrier
	ds_read_b64_tr_b16 v[196:197], v69 offset:24576
	ds_read_b64_tr_b16 v[198:199], v69 offset:25088
	v_add_f32_e32 v84, v132, v133
	v_add_f32_e32 v84, v134, v84
	v_add_f32_e32 v84, v135, v84
	v_add_f32_e32 v84, v136, v84
	v_add_f32_e32 v84, v137, v84
	v_cvt_pk_bf16_f32 v160, v132, v133
	v_cvt_pk_bf16_f32 v161, v134, v135
	s_waitcnt lgkmcnt(9)
	v_mfma_f32_32x32x16_bf16 v[100:115], v[92:95], v[176:179], 0
	v_add_f32_e32 v84, v138, v84
	v_add_f32_e32 v84, v139, v84
	v_add_f32_e32 v84, v140, v84
	v_add_f32_e32 v148, v141, v84
	s_waitcnt lgkmcnt(8)
	v_mfma_f32_32x32x16_bf16 v[84:99], v[96:99], v[176:179], 0
	v_cvt_pk_bf16_f32 v162, v136, v137
	v_cvt_pk_bf16_f32 v163, v138, v139
	ds_read_b64_tr_b16 v[132:133], v69 offset:25600
	ds_read_b64_tr_b16 v[134:135], v69 offset:26112
	s_waitcnt lgkmcnt(9)
	v_mfma_f32_32x32x16_bf16 v[100:115], v[76:79], v[172:175], v[100:115]
	v_add_f32_e32 v76, v142, v148
	v_add_f32_e32 v76, v143, v76
	v_add_f32_e32 v76, v144, v76
	v_add_f32_e32 v76, v145, v76
	v_cvt_pk_bf16_f32 v156, v140, v141
	v_cvt_pk_bf16_f32 v157, v142, v143
	s_waitcnt lgkmcnt(8)
	v_mfma_f32_32x32x16_bf16 v[84:99], v[180:183], v[172:175], v[84:99]
	v_add_f32_e32 v76, v146, v76
	v_add_f32_e32 v76, v147, v76
	v_add_f32_e32 v76, v116, v76
	v_add_f32_e32 v136, v117, v76
	v_cvt_pk_bf16_f32 v158, v144, v145
	v_cvt_pk_bf16_f32 v159, v146, v147
	ds_read_b64_tr_b16 v[76:77], v69 offset:26624
	ds_read_b64_tr_b16 v[78:79], v69 offset:27136
	s_waitcnt lgkmcnt(9)
	v_mfma_f32_32x32x16_bf16 v[100:115], v[80:83], v[168:171], v[100:115]
	v_add_f32_e32 v80, v118, v136
	v_add_f32_e32 v80, v119, v80
	v_add_f32_e32 v80, v120, v80
	v_add_f32_e32 v80, v121, v80
	v_cvt_pk_bf16_f32 v152, v116, v117
	v_cvt_pk_bf16_f32 v153, v118, v119
	s_waitcnt lgkmcnt(8)
	v_mfma_f32_32x32x16_bf16 v[84:99], v[184:187], v[168:171], v[84:99]
	v_add_f32_e32 v80, v122, v80
	v_add_f32_e32 v80, v123, v80
	v_add_f32_e32 v80, v124, v80
	v_add_f32_e32 v116, v125, v80
	v_cvt_pk_bf16_f32 v154, v120, v121
	v_cvt_pk_bf16_f32 v155, v122, v123
	ds_read_b64_tr_b16 v[80:81], v69 offset:27648
	ds_read_b64_tr_b16 v[82:83], v69 offset:28160
	s_waitcnt lgkmcnt(9)
	v_mfma_f32_32x32x16_bf16 v[100:115], v[188:191], v[164:167], v[100:115]
	v_add_f32_e32 v116, v126, v116
	v_add_f32_e32 v116, v127, v116
	v_add_f32_e32 v116, v128, v116
	v_add_f32_e32 v116, v129, v116
	v_cvt_pk_bf16_f32 v148, v124, v125
	v_cvt_pk_bf16_f32 v149, v126, v127
	s_waitcnt lgkmcnt(8)
	v_mfma_f32_32x32x16_bf16 v[84:99], v[192:195], v[164:167], v[84:99]
	v_add_f32_e32 v116, v130, v116
	v_add_f32_e32 v116, v131, v116
	v_add_f32_e32 v116, 0, v116
	v_cvt_pk_bf16_f32 v150, v128, v129
	v_cvt_pk_bf16_f32 v151, v130, v131
	s_add_i32 m0, s26, s0
	v_lshl_add_u64 v[74:75], v[74:75], 0, s[28:29]
	global_load_lds_dwordx4 v[74:75], off
	s_lshl_b32 s3, s24, 1
	s_add_i32 s3, s3, s1
	s_mov_b32 m0, s3
	v_lshl_add_u64 v[74:75], v[72:73], 0, s[66:67]
	global_load_lds_dwordx4 v[74:75], off
	s_add_i32 m0, s3, 0x2000
	v_lshl_add_u64 v[72:73], v[72:73], 0, s[72:73]
	global_load_lds_dwordx4 v[72:73], off
	v_add_f32_e32 v68, v68, v116
	s_waitcnt lgkmcnt(6)
	v_mfma_f32_32x32x16_bf16 v[36:51], v[160:163], v[196:199], v[36:51]
	v_exp_f32_e32 v100, v100
	v_exp_f32_e32 v101, v101
	ds_read_b64_tr_b16 v[72:73], v69 offset:28672
	ds_read_b64_tr_b16 v[74:75], v69 offset:29184
	s_waitcnt lgkmcnt(6)
	v_mfma_f32_32x32x16_bf16 v[36:51], v[156:159], v[132:135], v[36:51]
	v_exp_f32_e32 v102, v102
	v_exp_f32_e32 v103, v103
	ds_read_b64_tr_b16 v[116:117], v69 offset:29696
	ds_read_b64_tr_b16 v[118:119], v69 offset:30208
	s_waitcnt lgkmcnt(6)
	v_mfma_f32_32x32x16_bf16 v[36:51], v[152:155], v[76:79], v[36:51]
	v_exp_f32_e32 v104, v104
	v_exp_f32_e32 v105, v105
	ds_read_b64_tr_b16 v[76:77], v69 offset:30720
	ds_read_b64_tr_b16 v[78:79], v69 offset:31232
	s_waitcnt lgkmcnt(6)
	v_mfma_f32_32x32x16_bf16 v[36:51], v[148:151], v[80:83], v[36:51]
	v_exp_f32_e32 v106, v106
	v_exp_f32_e32 v107, v107
	ds_read_b64_tr_b16 v[80:81], v69 offset:31744
	ds_read_b64_tr_b16 v[82:83], v69 offset:32256
	s_waitcnt lgkmcnt(6)
	v_mfma_f32_32x32x16_bf16 v[52:67], v[160:163], v[72:75], v[52:67]
	v_exp_f32_e32 v108, v108
	v_exp_f32_e32 v109, v109
	ds_read_b64_tr_b16 v[72:73], v69 offset:32768
	ds_read_b64_tr_b16 v[74:75], v69 offset:33280
	s_waitcnt lgkmcnt(6)
	v_mfma_f32_32x32x16_bf16 v[52:67], v[156:159], v[116:119], v[52:67]
	v_exp_f32_e32 v110, v110
	v_exp_f32_e32 v111, v111
	ds_read_b64_tr_b16 v[116:117], v69 offset:33792
	ds_read_b64_tr_b16 v[118:119], v69 offset:34304
	s_waitcnt lgkmcnt(6)
	v_mfma_f32_32x32x16_bf16 v[52:67], v[152:155], v[76:79], v[52:67]
	v_exp_f32_e32 v112, v112
	v_exp_f32_e32 v113, v113
	ds_read_b64_tr_b16 v[76:77], v69 offset:34816
	ds_read_b64_tr_b16 v[78:79], v69 offset:35328
	s_waitcnt lgkmcnt(6)
	v_mfma_f32_32x32x16_bf16 v[52:67], v[148:151], v[80:83], v[52:67]
	v_exp_f32_e32 v114, v114
	v_exp_f32_e32 v115, v115
	ds_read_b64_tr_b16 v[80:81], v69 offset:35840
	ds_read_b64_tr_b16 v[82:83], v69 offset:36352
	s_waitcnt lgkmcnt(6)
	v_mfma_f32_32x32x16_bf16 v[4:19], v[160:163], v[72:75], v[4:19]
	v_exp_f32_e32 v84, v84
	v_exp_f32_e32 v85, v85
	ds_read_b64_tr_b16 v[72:73], v69 offset:36864
	ds_read_b64_tr_b16 v[74:75], v69 offset:37376
	s_waitcnt lgkmcnt(6)
	v_mfma_f32_32x32x16_bf16 v[4:19], v[156:159], v[116:119], v[4:19]
	v_exp_f32_e32 v86, v86
	v_exp_f32_e32 v87, v87
	ds_read_b64_tr_b16 v[116:117], v69 offset:37888
	ds_read_b64_tr_b16 v[118:119], v69 offset:38400
	s_waitcnt lgkmcnt(6)
	v_mfma_f32_32x32x16_bf16 v[4:19], v[152:155], v[76:79], v[4:19]
	v_exp_f32_e32 v88, v88
	v_exp_f32_e32 v89, v89
	ds_read_b64_tr_b16 v[76:77], v69 offset:38912
	ds_read_b64_tr_b16 v[78:79], v69 offset:39424
	s_waitcnt lgkmcnt(6)
	v_mfma_f32_32x32x16_bf16 v[4:19], v[148:151], v[80:83], v[4:19]
	v_exp_f32_e32 v90, v90
	v_exp_f32_e32 v91, v91
	ds_read_b64_tr_b16 v[80:81], v69 offset:39936
	ds_read_b64_tr_b16 v[82:83], v69 offset:40448
	v_add_u32_e32 v69, s24, v230
	ds_read_b128 v[208:211], v69
	ds_read_b128 v[200:203], v69 offset:512
	s_waitcnt lgkmcnt(8)
	v_mfma_f32_32x32x16_bf16 v[20:35], v[160:163], v[72:75], v[20:35]
	v_exp_f32_e32 v92, v92
	v_exp_f32_e32 v93, v93
	ds_read_b128 v[204:207], v69 offset:2048
	ds_read_b128 v[196:199], v69 offset:2560
	s_waitcnt lgkmcnt(8)
	v_mfma_f32_32x32x16_bf16 v[20:35], v[156:159], v[116:119], v[20:35]
	v_exp_f32_e32 v94, v94
	v_exp_f32_e32 v95, v95
	ds_read_b128 v[192:195], v69 offset:4096
	ds_read_b128 v[188:191], v69 offset:4608
	ds_read_b128 v[184:187], v69 offset:6144
	ds_read_b128 v[180:183], v69 offset:6656
	s_waitcnt lgkmcnt(10)
	v_mfma_f32_32x32x16_bf16 v[20:35], v[152:155], v[76:79], v[20:35]
	v_exp_f32_e32 v96, v96
	v_exp_f32_e32 v97, v97
	s_waitcnt lgkmcnt(8)
	v_mfma_f32_32x32x16_bf16 v[20:35], v[148:151], v[80:83], v[20:35]
	v_exp_f32_e32 v98, v98
	v_exp_f32_e32 v99, v99
	s_add_i32 s3, s24, 0x2000
	s_cmpk_lg_i32 s24, 0x4000
	s_cselect_b32 s26, s3, 0
	s_add_i32 s18, s2, 2
	s_add_u32 s14, s14, 0x20000
	s_addc_u32 s15, s15, 0
	s_mov_b32 s17, s16
	s_cmp_ge_u32 s18, s21
	s_waitcnt vmcnt(3) lgkmcnt(0)
	s_barrier
	s_cbranch_scc0 .LBB0_413
	s_add_i32 s64, s2, -3
	s_lshl_b64 s[12:13], s[12:13], 9
	s_add_i32 s2, s64, 1
	s_cmp_lt_u32 s2, s21
	s_cbranch_scc0 .LBB0_441
